# GEMM accumulator zeroing with v_mov_b64 (64 instead of 128 moves per tile)
# baseline (speedup 1.0000x reference)
; template <class Epi>
; DI void gemm_phase(LAS unsigned char* lds, const Gemm g, const Epi& E, const int tid) {
;     ...
;         const bool has_next = S.next(ui + 1, nxt);
;         const char* nA = has_next ? (const char*)g.A + (size_t)nxt.z * g.zA * 2 + (size_t)nxt.pm * 2 * hstepA + (nxt.pn >= g.pn_split ? (size_t)g.a_off2 * 2 : (size_t)0) : cA;
;         const char* nB = has_next ? (const char*)g.Bt + (size_t)nxt.z * g.zB * 2 + (size_t)nxt.pn * 2 * hstepB : cB;
;     ...
;         for (int a = 0; a < 2; ++a)
; #pragma unroll
;             for (int b = 0; b < 2; ++b)
; #pragma unroll
;                 for (int m = 0; m < 4; ++m)
; #pragma unroll
;                     for (int n = 0; n < 2; ++n) acc[a][b][m][n] = (f32x4){0.f, 0.f, 0.f, 0.f};
.LBB0_91:
	s_ashr_i32 s35, s34, 31
	s_lshl_b64 s[42:43], s[34:35], 15
	s_add_u32 s42, s30, s42
	s_addc_u32 s43, s31, s43
	s_and_b64 s[44:45], s[38:39], exec
	s_cselect_b32 s35, s43, s47
	s_cselect_b32 s63, s42, s46
	s_ashr_i32 s41, s40, 31
	s_lshl_b64 s[44:45], s[40:41], 21
	v_readlane_b32 s50, v252, 32
	v_readlane_b32 s51, v252, 33
	s_add_u32 s44, s50, s44
	s_addc_u32 s45, s51, s45
	s_and_b64 s[50:51], s[38:39], exec
	s_cselect_b32 s41, s45, s49
	s_cselect_b32 s64, s44, s48
	s_add_u32 s65, s48, 0x100
	s_addc_u32 s66, s49, 0
	s_add_u32 s46, s46, 0x804000
	s_addc_u32 s47, s47, 0
	s_mov_b32 s67, -2
	v_mov_b64_e32 v[2:3], 0
	v_mov_b64_e32 v[4:5], 0
	v_mov_b64_e32 v[6:7], 0
	v_mov_b64_e32 v[8:9], 0
	v_mov_b64_e32 v[10:11], 0
	v_mov_b64_e32 v[12:13], 0
	v_mov_b64_e32 v[14:15], 0
	v_mov_b64_e32 v[16:17], 0
	v_mov_b64_e32 v[18:19], 0
	v_mov_b64_e32 v[20:21], 0
	v_mov_b64_e32 v[22:23], 0
	v_mov_b64_e32 v[24:25], 0
	v_mov_b64_e32 v[26:27], 0
	v_mov_b64_e32 v[28:29], 0
	v_mov_b64_e32 v[30:31], 0
	v_mov_b64_e32 v[32:33], 0
	v_mov_b64_e32 v[34:35], 0
	v_mov_b64_e32 v[36:37], 0
	v_mov_b64_e32 v[38:39], 0
	v_mov_b64_e32 v[40:41], 0
	v_mov_b64_e32 v[42:43], 0
	v_mov_b64_e32 v[44:45], 0
	v_mov_b64_e32 v[46:47], 0
	v_mov_b64_e32 v[48:49], 0
	v_mov_b64_e32 v[50:51], 0
	v_mov_b64_e32 v[52:53], 0
	v_mov_b64_e32 v[54:55], 0
	v_mov_b64_e32 v[56:57], 0
	v_mov_b64_e32 v[58:59], 0
	v_mov_b64_e32 v[60:61], 0
	v_mov_b64_e32 v[62:63], 0
	v_mov_b64_e32 v[64:65], 0
	v_mov_b64_e32 v[66:67], 0
	v_mov_b64_e32 v[68:69], 0
	v_mov_b64_e32 v[70:71], 0
	v_mov_b64_e32 v[72:73], 0
	v_mov_b64_e32 v[74:75], 0
	v_mov_b64_e32 v[76:77], 0
	v_mov_b64_e32 v[78:79], 0
	v_mov_b64_e32 v[80:81], 0
	v_mov_b64_e32 v[82:83], 0
	v_mov_b64_e32 v[84:85], 0
	v_mov_b64_e32 v[86:87], 0
	v_mov_b64_e32 v[88:89], 0
	v_mov_b64_e32 v[90:91], 0
	v_mov_b64_e32 v[92:93], 0
	v_mov_b64_e32 v[94:95], 0
	v_mov_b64_e32 v[96:97], 0
	v_mov_b64_e32 v[98:99], 0
	v_mov_b64_e32 v[100:101], 0
	v_mov_b64_e32 v[102:103], 0
	v_mov_b64_e32 v[104:105], 0
	v_mov_b64_e32 v[106:107], 0
	v_mov_b64_e32 v[108:109], 0
	v_mov_b64_e32 v[110:111], 0
	v_mov_b64_e32 v[112:113], 0
	v_mov_b64_e32 v[114:115], 0
	v_mov_b64_e32 v[116:117], 0
	v_mov_b64_e32 v[118:119], 0
	v_mov_b64_e32 v[120:121], 0
	v_mov_b64_e32 v[122:123], 0
	v_mov_b64_e32 v[124:125], 0
	v_mov_b64_e32 v[126:127], 0
	v_mov_b64_e32 v[128:129], 0

; template <class Epi>
; DI void gemm_phase(LAS unsigned char* lds, const Gemm g, const Epi& E, const int tid) {
;     ...
;         const bool has_next = S.next(ui + 1, nxt);
;         const char* nA = has_next ? (const char*)g.A + (size_t)nxt.z * g.zA * 2 + (size_t)nxt.pm * 2 * hstepA + (nxt.pn >= g.pn_split ? (size_t)g.a_off2 * 2 : (size_t)0) : cA;
;         const char* nB = has_next ? (const char*)g.Bt + (size_t)nxt.z * g.zB * 2 + (size_t)nxt.pn * 2 * hstepB : cB;
;     ...
;         for (int a = 0; a < 2; ++a)
; #pragma unroll
;             for (int b = 0; b < 2; ++b)
; #pragma unroll
;                 for (int m = 0; m < 4; ++m)
; #pragma unroll
;                     for (int n = 0; n < 2; ++n) acc[a][b][m][n] = (f32x4){0.f, 0.f, 0.f, 0.f};
.LBB0_114:
	s_ashr_i32 s41, s40, 31
	s_lshl_b64 s[44:45], s[40:41], 19
	v_readlane_b32 s46, v252, 51
	v_readlane_b32 s47, v252, 52
	s_add_u32 s44, s46, s44
	s_addc_u32 s45, s47, s45
	s_and_b64 s[46:47], s[38:39], exec
	s_cselect_b32 s41, s45, s49
	s_cselect_b32 s64, s44, s48
	s_ashr_i32 s43, s42, 31
	s_lshl_b64 s[46:47], s[42:43], 19
	v_readlane_b32 s52, v252, 49
	v_readlane_b32 s53, v252, 50
	s_add_u32 s46, s52, s46
	s_addc_u32 s47, s53, s47
	s_and_b64 s[52:53], s[38:39], exec
	s_cselect_b32 s43, s47, s51
	s_cselect_b32 s65, s46, s50
	s_add_u32 s48, s48, 0x40080
	s_addc_u32 s49, s49, 0
	s_add_u32 s66, s50, 0x100
	s_addc_u32 s67, s51, 0
	s_mov_b32 s68, -2
	v_mov_b64_e32 v[2:3], 0
	v_mov_b64_e32 v[4:5], 0
	v_mov_b64_e32 v[6:7], 0
	v_mov_b64_e32 v[8:9], 0
	v_mov_b64_e32 v[10:11], 0
	v_mov_b64_e32 v[12:13], 0
	v_mov_b64_e32 v[14:15], 0
	v_mov_b64_e32 v[16:17], 0
	v_mov_b64_e32 v[18:19], 0
	v_mov_b64_e32 v[20:21], 0
	v_mov_b64_e32 v[22:23], 0
	v_mov_b64_e32 v[24:25], 0
	v_mov_b64_e32 v[26:27], 0
	v_mov_b64_e32 v[28:29], 0
	v_mov_b64_e32 v[30:31], 0
	v_mov_b64_e32 v[32:33], 0
	v_mov_b64_e32 v[34:35], 0
	v_mov_b64_e32 v[36:37], 0
	v_mov_b64_e32 v[38:39], 0
	v_mov_b64_e32 v[40:41], 0
	v_mov_b64_e32 v[42:43], 0
	v_mov_b64_e32 v[44:45], 0
	v_mov_b64_e32 v[46:47], 0
	v_mov_b64_e32 v[48:49], 0
	v_mov_b64_e32 v[50:51], 0
	v_mov_b64_e32 v[52:53], 0
	v_mov_b64_e32 v[54:55], 0
	v_mov_b64_e32 v[56:57], 0
	v_mov_b64_e32 v[58:59], 0
	v_mov_b64_e32 v[60:61], 0
	v_mov_b64_e32 v[62:63], 0
	v_mov_b64_e32 v[64:65], 0
	v_mov_b64_e32 v[66:67], 0
	v_mov_b64_e32 v[68:69], 0
	v_mov_b64_e32 v[70:71], 0
	v_mov_b64_e32 v[72:73], 0
	v_mov_b64_e32 v[74:75], 0
	v_mov_b64_e32 v[76:77], 0
	v_mov_b64_e32 v[78:79], 0
	v_mov_b64_e32 v[80:81], 0
	v_mov_b64_e32 v[82:83], 0
	v_mov_b64_e32 v[84:85], 0
	v_mov_b64_e32 v[86:87], 0
	v_mov_b64_e32 v[88:89], 0
	v_mov_b64_e32 v[90:91], 0
	v_mov_b64_e32 v[92:93], 0
	v_mov_b64_e32 v[94:95], 0
	v_mov_b64_e32 v[96:97], 0
	v_mov_b64_e32 v[98:99], 0
	v_mov_b64_e32 v[100:101], 0
	v_mov_b64_e32 v[102:103], 0
	v_mov_b64_e32 v[104:105], 0
	v_mov_b64_e32 v[106:107], 0
	v_mov_b64_e32 v[108:109], 0
	v_mov_b64_e32 v[110:111], 0
	v_mov_b64_e32 v[112:113], 0
	v_mov_b64_e32 v[114:115], 0
	v_mov_b64_e32 v[116:117], 0
	v_mov_b64_e32 v[118:119], 0
	v_mov_b64_e32 v[120:121], 0
	v_mov_b64_e32 v[122:123], 0
	v_mov_b64_e32 v[124:125], 0
	v_mov_b64_e32 v[126:127], 0
	v_mov_b64_e32 v[128:129], 0

; template <class Epi>
; DI void gemm_phase(LAS unsigned char* lds, const Gemm g, const Epi& E, const int tid) {
;     ...
;         const bool has_next = S.next(ui + 1, nxt);
;         const char* nA = has_next ? (const char*)g.A + (size_t)nxt.z * g.zA * 2 + (size_t)nxt.pm * 2 * hstepA + (nxt.pn >= g.pn_split ? (size_t)g.a_off2 * 2 : (size_t)0) : cA;
;         const char* nB = has_next ? (const char*)g.Bt + (size_t)nxt.z * g.zB * 2 + (size_t)nxt.pn * 2 * hstepB : cB;
;     ...
;         for (int a = 0; a < 2; ++a)
; #pragma unroll
;             for (int b = 0; b < 2; ++b)
; #pragma unroll
;                 for (int m = 0; m < 4; ++m)
; #pragma unroll
;                     for (int n = 0; n < 2; ++n) acc[a][b][m][n] = (f32x4){0.f, 0.f, 0.f, 0.f};
.LBB0_149:
	s_ashr_i32 s41, s40, 31
	s_lshl_b64 s[44:45], s[40:41], 19
	s_add_u32 s44, s36, s44
	s_addc_u32 s45, s37, s45
	s_and_b64 s[46:47], s[38:39], exec
	s_cselect_b32 s41, s45, s49
	s_cselect_b32 s64, s44, s48
	s_ashr_i32 s43, s42, 31
	s_lshl_b64 s[46:47], s[42:43], 19
	v_readlane_b32 s52, v253, 0
	v_readlane_b32 s53, v253, 1
	s_add_u32 s46, s52, s46
	s_addc_u32 s47, s53, s47
	s_and_b64 s[52:53], s[38:39], exec
	s_cselect_b32 s43, s47, s51
	s_cselect_b32 s65, s46, s50
	s_add_u32 s48, s48, 0x40080
	s_addc_u32 s49, s49, 0
	s_add_u32 s66, s50, 0x100
	s_addc_u32 s67, s51, 0
	s_mov_b32 s68, -2
	v_mov_b64_e32 v[2:3], 0
	v_mov_b64_e32 v[4:5], 0
	v_mov_b64_e32 v[6:7], 0
	v_mov_b64_e32 v[8:9], 0
	v_mov_b64_e32 v[10:11], 0
	v_mov_b64_e32 v[12:13], 0
	v_mov_b64_e32 v[14:15], 0
	v_mov_b64_e32 v[16:17], 0
	v_mov_b64_e32 v[18:19], 0
	v_mov_b64_e32 v[20:21], 0
	v_mov_b64_e32 v[22:23], 0
	v_mov_b64_e32 v[24:25], 0
	v_mov_b64_e32 v[26:27], 0
	v_mov_b64_e32 v[28:29], 0
	v_mov_b64_e32 v[30:31], 0
	v_mov_b64_e32 v[32:33], 0
	v_mov_b64_e32 v[34:35], 0
	v_mov_b64_e32 v[36:37], 0
	v_mov_b64_e32 v[38:39], 0
	v_mov_b64_e32 v[40:41], 0
	v_mov_b64_e32 v[42:43], 0
	v_mov_b64_e32 v[44:45], 0
	v_mov_b64_e32 v[46:47], 0
	v_mov_b64_e32 v[48:49], 0
	v_mov_b64_e32 v[50:51], 0
	v_mov_b64_e32 v[52:53], 0
	v_mov_b64_e32 v[54:55], 0
	v_mov_b64_e32 v[56:57], 0
	v_mov_b64_e32 v[58:59], 0
	v_mov_b64_e32 v[60:61], 0
	v_mov_b64_e32 v[62:63], 0
	v_mov_b64_e32 v[64:65], 0
	v_mov_b64_e32 v[66:67], 0
	v_mov_b64_e32 v[68:69], 0
	v_mov_b64_e32 v[70:71], 0
	v_mov_b64_e32 v[72:73], 0
	v_mov_b64_e32 v[74:75], 0
	v_mov_b64_e32 v[76:77], 0
	v_mov_b64_e32 v[78:79], 0
	v_mov_b64_e32 v[80:81], 0
	v_mov_b64_e32 v[82:83], 0
	v_mov_b64_e32 v[84:85], 0
	v_mov_b64_e32 v[86:87], 0
	v_mov_b64_e32 v[88:89], 0
	v_mov_b64_e32 v[90:91], 0
	v_mov_b64_e32 v[92:93], 0
	v_mov_b64_e32 v[94:95], 0
	v_mov_b64_e32 v[96:97], 0
	v_mov_b64_e32 v[98:99], 0
	v_mov_b64_e32 v[100:101], 0
	v_mov_b64_e32 v[102:103], 0
	v_mov_b64_e32 v[104:105], 0
	v_mov_b64_e32 v[106:107], 0
	v_mov_b64_e32 v[108:109], 0
	v_mov_b64_e32 v[110:111], 0
	v_mov_b64_e32 v[112:113], 0
	v_mov_b64_e32 v[114:115], 0
	v_mov_b64_e32 v[116:117], 0
	v_mov_b64_e32 v[118:119], 0
	v_mov_b64_e32 v[120:121], 0
	v_mov_b64_e32 v[122:123], 0
	v_mov_b64_e32 v[124:125], 0
	v_mov_b64_e32 v[126:127], 0
	v_mov_b64_e32 v[128:129], 0

; template <class Epi>
; DI void gemm_phase(LAS unsigned char* lds, const Gemm g, const Epi& E, const int tid) {
;     ...
;         const bool has_next = S.next(ui + 1, nxt);
;         const char* nA = has_next ? (const char*)g.A + (size_t)nxt.z * g.zA * 2 + (size_t)nxt.pm * 2 * hstepA + (nxt.pn >= g.pn_split ? (size_t)g.a_off2 * 2 : (size_t)0) : cA;
;         const char* nB = has_next ? (const char*)g.Bt + (size_t)nxt.z * g.zB * 2 + (size_t)nxt.pn * 2 * hstepB : cB;
;     ...
;         for (int a = 0; a < 2; ++a)
; #pragma unroll
;             for (int b = 0; b < 2; ++b)
; #pragma unroll
;                 for (int m = 0; m < 4; ++m)
; #pragma unroll
;                     for (int n = 0; n < 2; ++n) acc[a][b][m][n] = (f32x4){0.f, 0.f, 0.f, 0.f};
.LBB0_171:
	s_ashr_i32 s25, s24, 31
	s_lshl_b64 s[40:41], s[24:25], 19
	s_add_u32 s40, s50, s40
	s_addc_u32 s41, s51, s41
	s_and_b64 s[42:43], s[38:39], exec
	s_cselect_b32 s25, s41, s45
	s_cselect_b32 s62, s40, s44
	s_ashr_i32 s35, s34, 31
	s_lshl_b64 s[42:43], s[34:35], 19
	v_readlane_b32 s48, v253, 17
	v_readlane_b32 s49, v253, 18
	s_add_u32 s42, s48, s42
	s_addc_u32 s43, s49, s43
	s_and_b64 s[48:49], s[38:39], exec
	s_cselect_b32 s35, s43, s47
	s_cselect_b32 s63, s42, s46
	s_add_u32 s44, s44, 0x40080
	s_addc_u32 s45, s45, 0
	s_add_u32 s64, s46, 0x100
	s_addc_u32 s65, s47, 0
	s_mov_b32 s66, -2
	v_mov_b64_e32 v[2:3], 0
	v_mov_b64_e32 v[4:5], 0
	v_mov_b64_e32 v[6:7], 0
	v_mov_b64_e32 v[8:9], 0
	v_mov_b64_e32 v[10:11], 0
	v_mov_b64_e32 v[12:13], 0
	v_mov_b64_e32 v[14:15], 0
	v_mov_b64_e32 v[16:17], 0
	v_mov_b64_e32 v[18:19], 0
	v_mov_b64_e32 v[20:21], 0
	v_mov_b64_e32 v[22:23], 0
	v_mov_b64_e32 v[24:25], 0
	v_mov_b64_e32 v[26:27], 0
	v_mov_b64_e32 v[28:29], 0
	v_mov_b64_e32 v[30:31], 0
	v_mov_b64_e32 v[32:33], 0
	v_mov_b64_e32 v[34:35], 0
	v_mov_b64_e32 v[36:37], 0
	v_mov_b64_e32 v[38:39], 0
	v_mov_b64_e32 v[40:41], 0
	v_mov_b64_e32 v[42:43], 0
	v_mov_b64_e32 v[44:45], 0
	v_mov_b64_e32 v[46:47], 0
	v_mov_b64_e32 v[48:49], 0
	v_mov_b64_e32 v[50:51], 0
	v_mov_b64_e32 v[52:53], 0
	v_mov_b64_e32 v[54:55], 0
	v_mov_b64_e32 v[56:57], 0
	v_mov_b64_e32 v[58:59], 0
	v_mov_b64_e32 v[60:61], 0
	v_mov_b64_e32 v[62:63], 0
	v_mov_b64_e32 v[64:65], 0
	v_mov_b64_e32 v[66:67], 0
	v_mov_b64_e32 v[68:69], 0
	v_mov_b64_e32 v[70:71], 0
	v_mov_b64_e32 v[72:73], 0
	v_mov_b64_e32 v[74:75], 0
	v_mov_b64_e32 v[76:77], 0
	v_mov_b64_e32 v[78:79], 0
	v_mov_b64_e32 v[80:81], 0
	v_mov_b64_e32 v[82:83], 0
	v_mov_b64_e32 v[84:85], 0
	v_mov_b64_e32 v[86:87], 0
	v_mov_b64_e32 v[88:89], 0
	v_mov_b64_e32 v[90:91], 0
	v_mov_b64_e32 v[92:93], 0
	v_mov_b64_e32 v[94:95], 0
	v_mov_b64_e32 v[96:97], 0
	v_mov_b64_e32 v[98:99], 0
	v_mov_b64_e32 v[100:101], 0
	v_mov_b64_e32 v[102:103], 0
	v_mov_b64_e32 v[104:105], 0
	v_mov_b64_e32 v[106:107], 0
	v_mov_b64_e32 v[108:109], 0
	v_mov_b64_e32 v[110:111], 0
	v_mov_b64_e32 v[112:113], 0
	v_mov_b64_e32 v[114:115], 0
	v_mov_b64_e32 v[116:117], 0
	v_mov_b64_e32 v[118:119], 0
	v_mov_b64_e32 v[120:121], 0
	v_mov_b64_e32 v[122:123], 0
	v_mov_b64_e32 v[124:125], 0
	v_mov_b64_e32 v[126:127], 0
	v_mov_b64_e32 v[128:129], 0

; template <class Epi>
; DI void gemm_phase(LAS unsigned char* lds, const Gemm g, const Epi& E, const int tid) {
;     ...
;         const bool has_next = S.next(ui + 1, nxt);
;         const char* nA = has_next ? (const char*)g.A + (size_t)nxt.z * g.zA * 2 + (size_t)nxt.pm * 2 * hstepA + (nxt.pn >= g.pn_split ? (size_t)g.a_off2 * 2 : (size_t)0) : cA;
;         const char* nB = has_next ? (const char*)g.Bt + (size_t)nxt.z * g.zB * 2 + (size_t)nxt.pn * 2 * hstepB : cB;
;     ...
;         for (int a = 0; a < 2; ++a)
; #pragma unroll
;             for (int b = 0; b < 2; ++b)
; #pragma unroll
;                 for (int m = 0; m < 4; ++m)
; #pragma unroll
;                     for (int n = 0; n < 2; ++n) acc[a][b][m][n] = (f32x4){0.f, 0.f, 0.f, 0.f};
.LBB0_194:
	s_ashr_i32 s25, s24, 31
	s_lshl_b64 s[42:43], s[24:25], 10
	v_readlane_b32 s44, v251, 62
	v_readlane_b32 s45, v251, 63
	s_add_u32 s12, s44, s42
	s_addc_u32 s41, s45, s43
	s_ashr_i32 s35, s34, 31
	s_lshl_b64 s[42:43], s[34:35], 20
	s_add_u32 s42, s12, s42
	s_addc_u32 s43, s41, s43
	s_and_b64 s[44:45], s[38:39], exec
	s_cselect_b32 s35, s43, s47
	s_cselect_b32 s62, s42, s46
	s_lshl_b64 s[44:45], s[24:25], 20
	v_readlane_b32 s50, v251, 39
	v_readlane_b32 s51, v251, 40
	s_add_u32 s12, s50, s44
	s_addc_u32 s25, s51, s45
	s_ashr_i32 s41, s40, 31
	s_lshl_b64 s[44:45], s[40:41], 18
	s_add_u32 s44, s12, s44
	s_addc_u32 s45, s25, s45
	s_and_b64 s[50:51], s[38:39], exec
	s_cselect_b32 s25, s45, s49
	s_cselect_b32 s41, s44, s48
	s_add_u32 s46, s46, 0x80080
	s_addc_u32 s47, s47, 0
	s_add_u32 s63, s48, 0x100
	s_addc_u32 s64, s49, 0
	s_mov_b32 s65, -2
	v_mov_b64_e32 v[2:3], 0
	v_mov_b64_e32 v[4:5], 0
	v_mov_b64_e32 v[6:7], 0
	v_mov_b64_e32 v[8:9], 0
	v_mov_b64_e32 v[10:11], 0
	v_mov_b64_e32 v[12:13], 0
	v_mov_b64_e32 v[14:15], 0
	v_mov_b64_e32 v[16:17], 0
	v_mov_b64_e32 v[18:19], 0
	v_mov_b64_e32 v[20:21], 0
	v_mov_b64_e32 v[22:23], 0
	v_mov_b64_e32 v[24:25], 0
	v_mov_b64_e32 v[26:27], 0
	v_mov_b64_e32 v[28:29], 0
	v_mov_b64_e32 v[30:31], 0
	v_mov_b64_e32 v[32:33], 0
	v_mov_b64_e32 v[34:35], 0
	v_mov_b64_e32 v[36:37], 0
	v_mov_b64_e32 v[38:39], 0
	v_mov_b64_e32 v[40:41], 0
	v_mov_b64_e32 v[42:43], 0
	v_mov_b64_e32 v[44:45], 0
	v_mov_b64_e32 v[46:47], 0
	v_mov_b64_e32 v[48:49], 0
	v_mov_b64_e32 v[50:51], 0
	v_mov_b64_e32 v[52:53], 0
	v_mov_b64_e32 v[54:55], 0
	v_mov_b64_e32 v[56:57], 0
	v_mov_b64_e32 v[58:59], 0
	v_mov_b64_e32 v[60:61], 0
	v_mov_b64_e32 v[62:63], 0
	v_mov_b64_e32 v[64:65], 0
	v_mov_b64_e32 v[66:67], 0
	v_mov_b64_e32 v[68:69], 0
	v_mov_b64_e32 v[70:71], 0
	v_mov_b64_e32 v[72:73], 0
	v_mov_b64_e32 v[74:75], 0
	v_mov_b64_e32 v[76:77], 0
	v_mov_b64_e32 v[78:79], 0
	v_mov_b64_e32 v[80:81], 0
	v_mov_b64_e32 v[82:83], 0
	v_mov_b64_e32 v[84:85], 0
	v_mov_b64_e32 v[86:87], 0
	v_mov_b64_e32 v[88:89], 0
	v_mov_b64_e32 v[90:91], 0
	v_mov_b64_e32 v[92:93], 0
	v_mov_b64_e32 v[94:95], 0
	v_mov_b64_e32 v[96:97], 0
	v_mov_b64_e32 v[98:99], 0
	v_mov_b64_e32 v[100:101], 0
	v_mov_b64_e32 v[102:103], 0
	v_mov_b64_e32 v[104:105], 0
	v_mov_b64_e32 v[106:107], 0
	v_mov_b64_e32 v[108:109], 0
	v_mov_b64_e32 v[110:111], 0
	v_mov_b64_e32 v[112:113], 0
	v_mov_b64_e32 v[114:115], 0
	v_mov_b64_e32 v[116:117], 0
	v_mov_b64_e32 v[118:119], 0
	v_mov_b64_e32 v[120:121], 0
	v_mov_b64_e32 v[122:123], 0
	v_mov_b64_e32 v[124:125], 0
	v_mov_b64_e32 v[126:127], 0
	v_mov_b64_e32 v[128:129], 0

; template <class Epi>
; DI void gemm_phase(LAS unsigned char* lds, const Gemm g, const Epi& E, const int tid) {
;     ...
;         const bool has_next = S.next(ui + 1, nxt);
;         const char* nA = has_next ? (const char*)g.A + (size_t)nxt.z * g.zA * 2 + (size_t)nxt.pm * 2 * hstepA + (nxt.pn >= g.pn_split ? (size_t)g.a_off2 * 2 : (size_t)0) : cA;
;         const char* nB = has_next ? (const char*)g.Bt + (size_t)nxt.z * g.zB * 2 + (size_t)nxt.pn * 2 * hstepB : cB;
;     ...
;         for (int a = 0; a < 2; ++a)
; #pragma unroll
;             for (int b = 0; b < 2; ++b)
; #pragma unroll
;                 for (int m = 0; m < 4; ++m)
; #pragma unroll
;                     for (int n = 0; n < 2; ++n) acc[a][b][m][n] = (f32x4){0.f, 0.f, 0.f, 0.f};
.LBB0_359:
	s_ashr_i32 s35, s34, 31
	s_lshl_b64 s[42:43], s[34:35], 17
	v_readlane_b32 s48, v251, 59
	v_readlane_b32 s49, v251, 60
	s_add_u32 s42, s48, s42
	s_addc_u32 s43, s49, s43
	s_and_b64 s[38:39], s[38:39], exec
	s_cselect_b32 s35, s43, s45
	s_cselect_b32 s70, s42, s44
	s_mov_b32 s50, 0
	s_mov_b64 s[38:39], -1
	s_mov_b64 s[48:49], 0
	v_mov_b64_e32 v[2:3], 0
	v_mov_b64_e32 v[4:5], 0
	v_mov_b64_e32 v[6:7], 0
	v_mov_b64_e32 v[8:9], 0
	v_mov_b64_e32 v[10:11], 0
	v_mov_b64_e32 v[12:13], 0
	v_mov_b64_e32 v[14:15], 0
	v_mov_b64_e32 v[16:17], 0
	v_mov_b64_e32 v[18:19], 0
	v_mov_b64_e32 v[20:21], 0
	v_mov_b64_e32 v[22:23], 0
	v_mov_b64_e32 v[24:25], 0
	v_mov_b64_e32 v[26:27], 0
	v_mov_b64_e32 v[28:29], 0
	v_mov_b64_e32 v[30:31], 0
	v_mov_b64_e32 v[32:33], 0
	v_mov_b64_e32 v[34:35], 0
	v_mov_b64_e32 v[36:37], 0
	v_mov_b64_e32 v[38:39], 0
	v_mov_b64_e32 v[40:41], 0
	v_mov_b64_e32 v[42:43], 0
	v_mov_b64_e32 v[44:45], 0
	v_mov_b64_e32 v[46:47], 0
	v_mov_b64_e32 v[48:49], 0
	v_mov_b64_e32 v[50:51], 0
	v_mov_b64_e32 v[52:53], 0
	v_mov_b64_e32 v[54:55], 0
	v_mov_b64_e32 v[56:57], 0
	v_mov_b64_e32 v[58:59], 0
	v_mov_b64_e32 v[60:61], 0
	v_mov_b64_e32 v[62:63], 0
	v_mov_b64_e32 v[64:65], 0
	v_mov_b64_e32 v[66:67], 0
	v_mov_b64_e32 v[68:69], 0
	v_mov_b64_e32 v[70:71], 0
	v_mov_b64_e32 v[72:73], 0
	v_mov_b64_e32 v[74:75], 0
	v_mov_b64_e32 v[76:77], 0
	v_mov_b64_e32 v[78:79], 0
	v_mov_b64_e32 v[80:81], 0
	v_mov_b64_e32 v[82:83], 0
	v_mov_b64_e32 v[84:85], 0
	v_mov_b64_e32 v[86:87], 0
	v_mov_b64_e32 v[88:89], 0
	v_mov_b64_e32 v[90:91], 0
	v_mov_b64_e32 v[92:93], 0
	v_mov_b64_e32 v[94:95], 0
	v_mov_b64_e32 v[96:97], 0
	v_mov_b64_e32 v[98:99], 0
	v_mov_b64_e32 v[100:101], 0
	v_mov_b64_e32 v[102:103], 0
	v_mov_b64_e32 v[104:105], 0
	v_mov_b64_e32 v[106:107], 0
	v_mov_b64_e32 v[108:109], 0
	v_mov_b64_e32 v[110:111], 0
	v_mov_b64_e32 v[112:113], 0
	v_mov_b64_e32 v[114:115], 0
	v_mov_b64_e32 v[116:117], 0
	v_mov_b64_e32 v[118:119], 0
	v_mov_b64_e32 v[120:121], 0
	v_mov_b64_e32 v[122:123], 0
	v_mov_b64_e32 v[124:125], 0
	v_mov_b64_e32 v[126:127], 0
	v_mov_b64_e32 v[128:129], 0

; template <class Epi>
; DI void gemm_phase(LAS unsigned char* lds, const Gemm g, const Epi& E, const int tid) {
;     ...
;         const bool has_next = S.next(ui + 1, nxt);
;         const char* nA = has_next ? (const char*)g.A + (size_t)nxt.z * g.zA * 2 + (size_t)nxt.pm * 2 * hstepA + (nxt.pn >= g.pn_split ? (size_t)g.a_off2 * 2 : (size_t)0) : cA;
;         const char* nB = has_next ? (const char*)g.Bt + (size_t)nxt.z * g.zB * 2 + (size_t)nxt.pn * 2 * hstepB : cB;
;     ...
;         for (int a = 0; a < 2; ++a)
; #pragma unroll
;             for (int b = 0; b < 2; ++b)
; #pragma unroll
;                 for (int m = 0; m < 4; ++m)
; #pragma unroll
;                     for (int n = 0; n < 2; ++n) acc[a][b][m][n] = (f32x4){0.f, 0.f, 0.f, 0.f};
.LBB0_522:
	s_ashr_i32 s35, s34, 31
	s_lshl_b64 s[44:45], s[34:35], 19
	s_add_u32 s44, s4, s44
	s_addc_u32 s45, s13, s45
	s_and_b64 s[46:47], s[38:39], exec
	s_cselect_b32 s35, s45, s1
	s_cselect_b32 s60, s44, s0
	s_ashr_i32 s43, s42, 31
	s_lshl_b64 s[46:47], s[42:43], 19
	v_readlane_b32 s48, v253, 41
	v_readlane_b32 s49, v253, 42
	s_add_u32 s46, s48, s46
	s_addc_u32 s47, s49, s47
	s_and_b64 s[48:49], s[38:39], exec
	s_cselect_b32 s43, s47, s41
	s_cselect_b32 s61, s46, s40
	s_add_u32 s0, s0, 0x40080
	s_addc_u32 s1, s1, 0
	s_add_u32 s62, s40, 0x100
	s_addc_u32 s63, s41, 0
	s_mov_b32 s64, -2
	v_mov_b64_e32 v[2:3], 0
	v_mov_b64_e32 v[4:5], 0
	v_mov_b64_e32 v[6:7], 0
	v_mov_b64_e32 v[8:9], 0
	v_mov_b64_e32 v[10:11], 0
	v_mov_b64_e32 v[12:13], 0
	v_mov_b64_e32 v[14:15], 0
	v_mov_b64_e32 v[16:17], 0
	v_mov_b64_e32 v[18:19], 0
	v_mov_b64_e32 v[20:21], 0
	v_mov_b64_e32 v[22:23], 0
	v_mov_b64_e32 v[24:25], 0
	v_mov_b64_e32 v[26:27], 0
	v_mov_b64_e32 v[28:29], 0
	v_mov_b64_e32 v[30:31], 0
	v_mov_b64_e32 v[32:33], 0
	v_mov_b64_e32 v[34:35], 0
	v_mov_b64_e32 v[36:37], 0
	v_mov_b64_e32 v[38:39], 0
	v_mov_b64_e32 v[40:41], 0
	v_mov_b64_e32 v[42:43], 0
	v_mov_b64_e32 v[44:45], 0
	v_mov_b64_e32 v[46:47], 0
	v_mov_b64_e32 v[48:49], 0
	v_mov_b64_e32 v[50:51], 0
	v_mov_b64_e32 v[52:53], 0
	v_mov_b64_e32 v[54:55], 0
	v_mov_b64_e32 v[56:57], 0
	v_mov_b64_e32 v[58:59], 0
	v_mov_b64_e32 v[60:61], 0
	v_mov_b64_e32 v[62:63], 0
	v_mov_b64_e32 v[64:65], 0
	v_mov_b64_e32 v[66:67], 0
	v_mov_b64_e32 v[68:69], 0
	v_mov_b64_e32 v[70:71], 0
	v_mov_b64_e32 v[72:73], 0
	v_mov_b64_e32 v[74:75], 0
	v_mov_b64_e32 v[76:77], 0
	v_mov_b64_e32 v[78:79], 0
	v_mov_b64_e32 v[80:81], 0
	v_mov_b64_e32 v[82:83], 0
	v_mov_b64_e32 v[84:85], 0
	v_mov_b64_e32 v[86:87], 0
	v_mov_b64_e32 v[88:89], 0
	v_mov_b64_e32 v[90:91], 0
	v_mov_b64_e32 v[92:93], 0
	v_mov_b64_e32 v[94:95], 0
	v_mov_b64_e32 v[96:97], 0
	v_mov_b64_e32 v[98:99], 0
	v_mov_b64_e32 v[100:101], 0
	v_mov_b64_e32 v[102:103], 0
	v_mov_b64_e32 v[104:105], 0
	v_mov_b64_e32 v[106:107], 0
	v_mov_b64_e32 v[108:109], 0
	v_mov_b64_e32 v[110:111], 0
	v_mov_b64_e32 v[112:113], 0
	v_mov_b64_e32 v[114:115], 0
	v_mov_b64_e32 v[116:117], 0
	v_mov_b64_e32 v[118:119], 0
	v_mov_b64_e32 v[120:121], 0
	v_mov_b64_e32 v[122:123], 0
	v_mov_b64_e32 v[124:125], 0
	v_mov_b64_e32 v[126:127], 0
	v_mov_b64_e32 v[128:129], 0
